# up-proj conv epilogue: removed dead row-address arithmetic left in the n=0 pass after its stores moved to the n=1 pass
# speedup vs baseline: 1.0111x; 1.0001x over previous
;     __device__ __forceinline__ void operator()(const f32x4 (&acc)[2][2][4][2], const Unit& u, int wr, int wc, int fr, int fq) const {
;     ...
;         __builtin_amdgcn_s_barrier(); asm volatile("" ::: "memory");
; #pragma unroll
;         for (int n = 0; n < 2; ++n) {
;             const int chg = 128 * u.pn + 32 * wc + 16 * n + 4 * fq;
;             if (n == 1) CG_LOADW(1);
;             f32x4 w0[2], w1[2], w2[2], bb[2], w0m[2], w2m[2];
; #pragma unroll
;             for (int bj = 0; bj < 2; ++bj) {
;                 w0[bj] = wq[n][bj][0]; w1[bj] = wq[n][bj][1]; w2[bj] = wq[n][bj][2]; bb[bj] = wq[n][bj][3];
;                 w0m[bj] = (fr == 0) ? w0[bj] : (f32x4){0.f, 0.f, 0.f, 0.f}; w2m[bj] = (fr == 15) ? w2[bj] : (f32x4){0.f, 0.f, 0.f, 0.f};
;             }
; #pragma unroll
;             for (int ai = 0; ai < 2; ++ai) {
;                 const int s = 2 * ai + wr;
;                 f32x4 xp[2], xn[2];
; #pragma unroll
;                 for (int bj = 0; bj < 2; ++bj) {
;                     xp[bj] = *(const LAS f32x4*)(X + ((((s + 3) & 3) * 2 + 1) * 2 + bj) * 128 + 32 * wc + 16 * n + 4 * fq);
;                     xn[bj] = *(const LAS f32x4*)(X + ((((s + 1) & 3) * 2 + 0) * 2 + bj) * 128 + 32 * wc + 16 * n + 4 * fq);
;                 }
;                 f32x4 cvv[4][2];
; #pragma unroll
;                 for (int bj = 0; bj < 2; ++bj) {
;                     const f32x4 a0 = acc[ai][bj][0][n], a1 = acc[ai][bj][1][n], a2 = acc[ai][bj][2][n], a3 = acc[ai][bj][3][n];
;                     f32x4 c0 = bb[bj] + w1[bj] * a0 + w2[bj] * a1 + w0m[bj] * xp[bj];
;                     f32x4 c1 = bb[bj] + w1[bj] * a1 + w0[bj] * a0 + w2[bj] * a2;
;                     f32x4 c2 = bb[bj] + w1[bj] * a2 + w0[bj] * a1 + w2[bj] * a3;
;                     f32x4 c3 = bb[bj] + w1[bj] * a3 + w0[bj] * a2 + w2m[bj] * xn[bj];
;                     DPP_FMAC4(c0, a3, w0[bj], "row_shr:1");
;                     DPP_FMAC4(c3, a0, w2[bj], "row_shl:1");
;                     cvv[0][bj] = c0; cvv[1][bj] = c1; cvv[2][bj] = c2; cvv[3][bj] = c3;
;                 }
; #pragma unroll
;                 for (int m = 0; m < 4; ++m) {
;                     const int lr = 128 * ai + 64 * wr + 4 * fr + m;
;                     const int R = 254 * u.pm + lr;
;                     const int b = R >= (H2_BSTRIDE + 1) ? 1 : 0;
;                     const int t = R - 1 - H2_BSTRIDE * b;
.LBB0_1014:
	s_or_b64 exec, exec, s[12:13]
	v_lshlrev_b32_e32 v196, 2, v168
	s_waitcnt lgkmcnt(0)
	s_barrier
	v_add_u32_e32 v222, s80, v196
	v_add_u32_e32 v219, s88, v196
	v_cmp_eq_u32_e32 vcc, 0, v180
	v_add_u32_e32 v220, s83, v222
	ds_read_b128 v[196:199], v219 offset:1024
	ds_read_b128 v[200:203], v219 offset:1536
	ds_read_b128 v[208:211], v220
	ds_read_b128 v[226:229], v220 offset:512
	s_waitcnt vmcnt(0)
	v_pk_fma_f32 v[206:207], v[124:125], v[148:149], v[152:153]
	v_cndmask_b32_e32 v195, 0, v141, vcc
	v_cndmask_b32_e32 v194, 0, v140, vcc
	v_pk_fma_f32 v[206:207], v[116:117], v[136:137], v[206:207]
	v_cmp_eq_u32_e64 s[8:9], 15, v180
	v_pk_fma_f32 v[204:205], v[126:127], v[150:151], v[154:155]
	s_waitcnt lgkmcnt(0)
	v_pk_fma_f32 v[206:207], v[194:195], v[196:197], v[206:207]
	v_pk_fma_f32 v[196:197], v[110:111], v[150:151], v[154:155]
	v_cndmask_b32_e32 v193, 0, v143, vcc
	v_cndmask_b32_e32 v192, 0, v142, vcc
	v_cndmask_b32_e64 v189, 0, v139, s[8:9]
	v_cndmask_b32_e64 v188, 0, v138, s[8:9]
	v_pk_fma_f32 v[204:205], v[118:119], v[138:139], v[204:205]
	v_pk_fma_f32 v[196:197], v[114:115], v[142:143], v[196:197]
	v_pk_fma_f32 v[204:205], v[192:193], v[198:199], v[204:205]
	v_pk_fma_f32 v[198:199], v[108:109], v[148:149], v[152:153]
	v_pk_fma_f32 v[196:197], v[188:189], v[210:211], v[196:197]
	v_pk_fma_f32 v[210:211], v[120:121], v[144:145], v[156:157]
	v_cndmask_b32_e64 v191, 0, v137, s[8:9]
	v_cndmask_b32_e64 v190, 0, v136, s[8:9]
	v_cndmask_b32_e32 v187, 0, v133, vcc
	v_cndmask_b32_e32 v186, 0, v132, vcc
	v_pk_fma_f32 v[198:199], v[112:113], v[140:141], v[198:199]
	v_pk_fma_f32 v[210:211], v[104:105], v[128:129], v[210:211]
	v_pk_fma_f32 v[198:199], v[190:191], v[208:209], v[198:199]
	v_pk_fma_f32 v[208:209], v[122:123], v[146:147], v[158:159]
	v_pk_fma_f32 v[210:211], v[186:187], v[200:201], v[210:211]
	v_pk_fma_f32 v[200:201], v[98:99], v[146:147], v[158:159]
	v_lshl_or_b32 v221, v180, 2, s75
	v_cndmask_b32_e32 v185, 0, v135, vcc
	v_cndmask_b32_e32 v184, 0, v134, vcc
	v_cndmask_b32_e64 v181, 0, v131, s[8:9]
	v_cndmask_b32_e64 v180, 0, v130, s[8:9]
	v_pk_fma_f32 v[208:209], v[106:107], v[130:131], v[208:209]
	v_pk_fma_f32 v[200:201], v[102:103], v[134:135], v[200:201]
	s_mul_i32 s41, s47, 0xfe
	v_pk_fma_f32 v[208:209], v[184:185], v[202:203], v[208:209]
	v_pk_fma_f32 v[202:203], v[96:97], v[144:145], v[156:157]
	v_pk_fma_f32 v[200:201], v[180:181], v[228:229], v[200:201]
	v_cndmask_b32_e64 v183, 0, v129, s[8:9]
	v_cndmask_b32_e64 v182, 0, v128, s[8:9]
	v_mov_b32_e32 v223, v196
	v_pk_fma_f32 v[202:203], v[100:101], v[132:133], v[202:203]
	v_mov_b32_e32 v196, v209
	v_mov_b32_e32 v209, v201
	v_add_u32_e32 v201, s41, v221
	v_pk_fma_f32 v[202:203], v[182:183], v[226:227], v[202:203]
	v_cmp_lt_i32_e64 s[12:13], s93, v201
	v_mov_b32_e32 v224, v198
	v_mov_b32_e32 v198, v210
	v_mov_b32_e32 v210, v203
	v_cndmask_b32_e64 v203, 0, v217, s[12:13]
	v_add_u32_e32 v201, v201, v203
	v_mov_b32_e32 v212, v204
	v_add_u32_e32 v204, -1, v201
	v_add_u32_e32 v201, -1, v221
	v_cmp_gt_u32_e64 s[14:15], s92, v201
	v_cmp_gt_u32_e64 s[16:17], s74, v204
	v_mov_b32_e32 v225, v206
	s_and_b64 s[48:49], s[14:15], s[16:17]
	v_cndmask_b32_e64 v206, 0, v218, s[12:13]
	s_nop 1
	v_fmac_f32_dpp v225, v108, v140 row_shr:1 row_mask:0xf bank_mask:0xf bound_ctrl:1
	v_fmac_f32_dpp v207, v109, v141 row_shr:1 row_mask:0xf bank_mask:0xf bound_ctrl:1
	v_fmac_f32_dpp v212, v110, v142 row_shr:1 row_mask:0xf bank_mask:0xf bound_ctrl:1
	v_fmac_f32_dpp v205, v111, v143 row_shr:1 row_mask:0xf bank_mask:0xf bound_ctrl:1
	s_nop 1
	v_fmac_f32_dpp v224, v124, v136 row_shl:1 row_mask:0xf bank_mask:0xf bound_ctrl:1
	v_fmac_f32_dpp v199, v125, v137 row_shl:1 row_mask:0xf bank_mask:0xf bound_ctrl:1
	v_fmac_f32_dpp v223, v126, v138 row_shl:1 row_mask:0xf bank_mask:0xf bound_ctrl:1
	v_fmac_f32_dpp v197, v127, v139 row_shl:1 row_mask:0xf bank_mask:0xf bound_ctrl:1
	s_nop 1
	v_fmac_f32_dpp v198, v96, v132 row_shr:1 row_mask:0xf bank_mask:0xf bound_ctrl:1
	v_fmac_f32_dpp v211, v97, v133 row_shr:1 row_mask:0xf bank_mask:0xf bound_ctrl:1
	v_fmac_f32_dpp v208, v98, v134 row_shr:1 row_mask:0xf bank_mask:0xf bound_ctrl:1
	v_fmac_f32_dpp v196, v99, v135 row_shr:1 row_mask:0xf bank_mask:0xf bound_ctrl:1
	s_nop 1
	v_fmac_f32_dpp v202, v120, v128 row_shl:1 row_mask:0xf bank_mask:0xf bound_ctrl:1
	v_fmac_f32_dpp v210, v121, v129 row_shl:1 row_mask:0xf bank_mask:0xf bound_ctrl:1
	v_fmac_f32_dpp v200, v122, v130 row_shl:1 row_mask:0xf bank_mask:0xf bound_ctrl:1
	v_fmac_f32_dpp v209, v123, v131 row_shl:1 row_mask:0xf bank_mask:0xf bound_ctrl:1
	s_and_saveexec_b64 s[12:13], s[48:49]
	s_cbranch_execz .LBB0_1016
	v_mul_f32_e32 v201, 0xbfb8aa3b, v225
	v_mul_f32_e32 v203, 0xbfb8aa3b, v207
	v_exp_f32_e32 v201, v201
	v_exp_f32_e32 v203, v203
	v_mul_f32_e32 v226, 0xbfb8aa3b, v212
	v_mov_b32_e32 v229, v169
	v_add_f32_e32 v201, 1.0, v201
	v_add_f32_e32 v203, 1.0, v203
	v_rcp_f32_e32 v201, v201
	v_rcp_f32_e32 v203, v203
	v_mul_f32_e32 v201, v225, v201
	v_mul_f32_e32 v203, v207, v203
	v_mul_f32_e32 v207, 0xbfb8aa3b, v205
	v_mul_f32_e32 v198, v198, v201
	v_exp_f32_e32 v201, v226
	v_exp_f32_e32 v207, v207
	v_mul_f32_e32 v203, v211, v203
	v_cvt_pk_bf16_f32 v230, v198, v203
	v_add_f32_e32 v201, 1.0, v201
	v_add_f32_e32 v207, 1.0, v207
	v_rcp_f32_e32 v201, v201
	v_rcp_f32_e32 v207, v207
	v_mul_f32_e32 v198, v212, v201
	v_mul_f32_e32 v201, v205, v207
	v_mul_f32_e32 v196, v196, v201
	v_mul_f32_e32 v198, v208, v198
	v_cvt_pk_bf16_f32 v231, v198, v196
; __device__ __forceinline__ unsigned pk2(float lo, float hi) { unsigned r; asm("v_cvt_pk_bf16_f32 %0, %1, %2" : "=v"(r) : "v"(lo), "v"(hi)); return r; }
; __device__ __forceinline__ float silu_(float x) { return x * fast_sigmoid(x); }
;     __device__ __forceinline__ void operator()(const f32x4 (&acc)[2][2][4][2], const Unit& u, int wr, int wc, int fr, int fq) const {
;     ...
;                 for (int m = 0; m < 4; ++m) {
;                     const int lr = 128 * ai + 64 * wr + 4 * fr + m;
;                     const int R = 254 * u.pm + lr;
;                     const int b = R >= (H2_BSTRIDE + 1) ? 1 : 0;
;                     const int t = R - 1 - H2_BSTRIDE * b;
;                     const bool valid = lr >= 1 && lr <= 254 && t >= 0 && t < S;
;                     if (valid) {
;                         u32x2 w;
;                         w.x = pk2(silu_(cvv[m][0][0]) * cvv[m][1][0], silu_(cvv[m][0][1]) * cvv[m][1][1]);
;                         w.y = pk2(silu_(cvv[m][0][2]) * cvv[m][1][2], silu_(cvv[m][0][3]) * cvv[m][1][3]);
;                         *(u32x2*)(act + (size_t)(b * S + t) * DFF + chg) = w;
.LBB0_1016:
	s_or_b64 exec, exec, s[12:13]
	v_add3_u32 v196, s41, v221, 1
	v_cmp_lt_i32_e64 s[12:13], s93, v196
	v_cmp_gt_u32_e64 s[14:15], s92, v221
	s_nop 0
	v_cndmask_b32_e64 v198, 0, v217, s[12:13]
	v_add_u32_e32 v196, v196, v198
	v_add_u32_e32 v196, -1, v196
	v_cmp_gt_u32_e64 s[16:17], s74, v196
	s_and_b64 s[50:51], s[14:15], s[16:17]
	v_cndmask_b32_e64 v198, 0, v218, s[12:13]
	s_and_saveexec_b64 s[12:13], s[50:51]
	s_cbranch_execz .LBB0_1018
	v_pk_fma_f32 v[228:229], v[116:117], v[148:149], v[152:153]
	v_pk_fma_f32 v[226:227], v[118:119], v[150:151], v[154:155]
	v_pk_fma_f32 v[124:125], v[124:125], v[140:141], v[228:229]
	v_pk_fma_f32 v[228:229], v[104:105], v[144:145], v[156:157]
	v_pk_fma_f32 v[124:125], v[112:113], v[136:137], v[124:125]
	v_pk_fma_f32 v[126:127], v[126:127], v[142:143], v[226:227]
	v_mul_f32_e32 v201, 0xbfb8aa3b, v124
	v_exp_f32_e32 v201, v201
	v_mul_f32_e32 v203, 0xbfb8aa3b, v125
	v_exp_f32_e32 v203, v203
	v_pk_fma_f32 v[120:121], v[120:121], v[132:133], v[228:229]
	v_add_f32_e32 v201, 1.0, v201
	v_rcp_f32_e32 v201, v201
	v_add_f32_e32 v203, 1.0, v203
	v_rcp_f32_e32 v203, v203
	v_pk_fma_f32 v[126:127], v[114:115], v[138:139], v[126:127]
	v_pk_fma_f32 v[120:121], v[100:101], v[128:129], v[120:121]
	v_mul_f32_e32 v124, v124, v201
	v_mul_f32_e32 v120, v120, v124
	v_mul_f32_e32 v124, v125, v203
	v_mul_f32_e32 v125, 0xbfb8aa3b, v126
	v_exp_f32_e32 v125, v125
	v_mul_f32_e32 v201, 0xbfb8aa3b, v127
	v_exp_f32_e32 v201, v201
	v_mul_f32_e32 v121, v121, v124
	v_add_f32_e32 v124, 1.0, v125
	v_rcp_f32_e32 v124, v124
	v_add_f32_e32 v125, 1.0, v201
	v_rcp_f32_e32 v125, v125
	v_pk_fma_f32 v[226:227], v[106:107], v[146:147], v[158:159]
	v_cvt_pk_bf16_f32 v232, v120, v121
	v_mul_f32_e32 v121, v126, v124
	v_pk_fma_f32 v[122:123], v[122:123], v[134:135], v[226:227]
	s_nop 0
	v_pk_fma_f32 v[122:123], v[102:103], v[130:131], v[122:123]
	s_nop 0
	v_mul_f32_e32 v121, v122, v121
	v_mul_f32_e32 v122, v127, v125
	v_mul_f32_e32 v122, v123, v122
	v_cvt_pk_bf16_f32 v233, v121, v122
.LBB0_1018:
	s_or_b64 exec, exec, s[12:13]
	v_or_b32_e32 v120, 2, v221
	v_add_u32_e32 v121, s41, v120
	v_cmp_lt_i32_e64 s[12:13], s93, v121
	v_cmp_gt_u32_e64 s[14:15], s95, v120
	s_nop 0
	v_cndmask_b32_e64 v122, 0, v217, s[12:13]
	v_add_u32_e32 v121, v121, v122
	v_add_u32_e32 v201, -1, v121
	v_cmp_gt_u32_e64 s[16:17], s74, v201
	s_and_b64 s[52:53], s[14:15], s[16:17]
	v_cndmask_b32_e64 v203, 0, v218, s[12:13]
	s_and_saveexec_b64 s[12:13], s[52:53]
	s_cbranch_execz .LBB0_1020
	v_pk_fma_f32 v[112:113], v[112:113], v[148:149], v[152:153]
	v_pk_fma_f32 v[100:101], v[100:101], v[144:145], v[156:157]
	v_pk_fma_f32 v[112:113], v[116:117], v[140:141], v[112:113]
	v_pk_fma_f32 v[100:101], v[104:105], v[132:133], v[100:101]
	v_pk_fma_f32 v[108:109], v[108:109], v[136:137], v[112:113]
	v_pk_fma_f32 v[102:103], v[102:103], v[146:147], v[158:159]
	v_mul_f32_e32 v104, 0xbfb8aa3b, v108
	v_exp_f32_e32 v104, v104
	v_mul_f32_e32 v105, 0xbfb8aa3b, v109
	v_pk_fma_f32 v[102:103], v[106:107], v[134:135], v[102:103]
	v_exp_f32_e32 v105, v105
	v_pk_fma_f32 v[98:99], v[98:99], v[130:131], v[102:103]
	v_add_f32_e32 v102, 1.0, v104
	v_pk_fma_f32 v[114:115], v[114:115], v[150:151], v[154:155]
	v_rcp_f32_e32 v102, v102
	v_pk_fma_f32 v[114:115], v[118:119], v[142:143], v[114:115]
	v_add_f32_e32 v103, 1.0, v105
	v_pk_fma_f32 v[110:111], v[110:111], v[138:139], v[114:115]
	v_rcp_f32_e32 v103, v103
	v_pk_fma_f32 v[96:97], v[96:97], v[128:129], v[100:101]
	v_mul_f32_e32 v101, 0xbfb8aa3b, v110
	v_mul_f32_e32 v100, v108, v102
	v_exp_f32_e32 v101, v101
	v_mul_f32_e32 v102, 0xbfb8aa3b, v111
	v_exp_f32_e32 v102, v102
	v_mul_f32_e32 v96, v96, v100
	v_mul_f32_e32 v100, v109, v103
	v_mul_f32_e32 v97, v97, v100
	v_add_f32_e32 v100, 1.0, v101
	v_rcp_f32_e32 v100, v100
	v_add_f32_e32 v101, 1.0, v102
	v_rcp_f32_e32 v101, v101
	v_cvt_pk_bf16_f32 v234, v96, v97
	v_mul_f32_e32 v97, v110, v100
	v_mul_f32_e32 v97, v98, v97
	v_mul_f32_e32 v98, v111, v101
	v_mul_f32_e32 v98, v99, v98
	v_cvt_pk_bf16_f32 v235, v97, v98
.LBB0_1020:
	s_or_b64 exec, exec, s[12:13]
	v_or_b32_e32 v96, 3, v221
	v_add_u32_e32 v97, s41, v96
	v_cmp_lt_i32_e64 s[12:13], s93, v97
	v_cmp_gt_u32_e64 s[14:15], s95, v96
	s_nop 0
	v_cndmask_b32_e64 v98, 0, v217, s[12:13]
	v_add_u32_e32 v97, v97, v98
	v_add_u32_e32 v205, -1, v97
	v_cmp_gt_u32_e64 s[16:17], s74, v205
	s_and_b64 s[54:55], s[14:15], s[16:17]
	v_cndmask_b32_e64 v207, 0, v218, s[12:13]
	s_and_saveexec_b64 s[12:13], s[54:55]
	s_cbranch_execz .LBB0_1022
	v_mul_f32_e32 v96, 0xbfb8aa3b, v224
	v_mul_f32_e32 v97, 0xbfb8aa3b, v199
	v_exp_f32_e32 v96, v96
	v_exp_f32_e32 v97, v97
	v_mul_f32_e32 v98, 0xbfb8aa3b, v223
	v_mul_f32_e32 v99, 0xbfb8aa3b, v197
	v_exp_f32_e32 v98, v98
	v_exp_f32_e32 v99, v99
	v_add_f32_e32 v96, 1.0, v96
	v_add_f32_e32 v97, 1.0, v97
	v_rcp_f32_e32 v96, v96
	v_rcp_f32_e32 v97, v97
	v_add_f32_e32 v98, 1.0, v98
	v_add_f32_e32 v99, 1.0, v99
	v_rcp_f32_e32 v98, v98
	v_rcp_f32_e32 v99, v99
	v_mul_f32_e32 v96, v224, v96
	v_mul_f32_e32 v97, v199, v97
	v_mul_f32_e32 v96, v202, v96
	v_mul_f32_e32 v97, v210, v97
	v_cvt_pk_bf16_f32 v236, v96, v97
	v_mul_f32_e32 v97, v223, v98
	v_mul_f32_e32 v98, v197, v99
	v_mul_f32_e32 v97, v200, v97
	v_mul_f32_e32 v98, v209, v98
	v_cvt_pk_bf16_f32 v237, v97, v98
; #define LAS __attribute__((address_space(3)))
; __device__ __forceinline__ unsigned pk2(float lo, float hi) { unsigned r; asm("v_cvt_pk_bf16_f32 %0, %1, %2" : "=v"(r) : "v"(lo), "v"(hi)); return r; }
;     __device__ __forceinline__ void operator()(const f32x4 (&acc)[2][2][4][2], const Unit& u, int wr, int wc, int fr, int fq) const {
;     ...
;             for (int ai = 0; ai < 2; ++ai) {
;                 const int s = 2 * ai + wr;
;                 f32x4 xp[2], xn[2];
; #pragma unroll
;                 for (int bj = 0; bj < 2; ++bj) {
;                     xp[bj] = *(const LAS f32x4*)(X + ((((s + 3) & 3) * 2 + 1) * 2 + bj) * 128 + 32 * wc + 16 * n + 4 * fq);
;                     xn[bj] = *(const LAS f32x4*)(X + ((((s + 1) & 3) * 2 + 0) * 2 + bj) * 128 + 32 * wc + 16 * n + 4 * fq);
;                 }
;                 f32x4 cvv[4][2];
; #pragma unroll
;                 for (int bj = 0; bj < 2; ++bj) {
;                     const f32x4 a0 = acc[ai][bj][0][n], a1 = acc[ai][bj][1][n], a2 = acc[ai][bj][2][n], a3 = acc[ai][bj][3][n];
;                     f32x4 c0 = bb[bj] + w1[bj] * a0 + w2[bj] * a1 + w0m[bj] * xp[bj];
;                     f32x4 c1 = bb[bj] + w1[bj] * a1 + w0[bj] * a0 + w2[bj] * a2;
;                     f32x4 c2 = bb[bj] + w1[bj] * a2 + w0[bj] * a1 + w2[bj] * a3;
;                     f32x4 c3 = bb[bj] + w1[bj] * a3 + w0[bj] * a2 + w2m[bj] * xn[bj];
;                     DPP_FMAC4(c0, a3, w0[bj], "row_shr:1");
;                     DPP_FMAC4(c3, a0, w2[bj], "row_shl:1");
;                     cvv[0][bj] = c0; cvv[1][bj] = c1; cvv[2][bj] = c2; cvv[3][bj] = c3;
;                 }
; #pragma unroll
;                 for (int m = 0; m < 4; ++m) {
;                     const int lr = 128 * ai + 64 * wr + 4 * fr + m;
;                     const int R = 254 * u.pm + lr;
;                     const int b = R >= (H2_BSTRIDE + 1) ? 1 : 0;
;                     const int t = R - 1 - H2_BSTRIDE * b;
;                     const bool valid = lr >= 1 && lr <= 254 && t >= 0 && t < S;
;                     if (valid) {
;                         u32x2 w;
;                         w.x = pk2(silu_(cvv[m][0][0]) * cvv[m][1][0], silu_(cvv[m][0][1]) * cvv[m][1][1]);
;                         w.y = pk2(silu_(cvv[m][0][2]) * cvv[m][1][2], silu_(cvv[m][0][3]) * cvv[m][1][3]);
;                         *(u32x2*)(act + (size_t)(b * S + t) * DFF + chg) = w;
.LBB0_1022:
	s_or_b64 exec, exec, s[12:13]
	v_lshl_add_u32 v197, v168, 2, s89
	v_add_u32_e32 v199, s82, v222
	ds_read_b128 v[96:99], v197 offset:1024
	ds_read_b128 v[100:103], v197 offset:1536
	ds_read_b128 v[108:111], v199
	ds_read_b128 v[112:115], v199 offset:512
	v_pk_fma_f32 v[104:105], v[94:95], v[150:151], v[154:155]
	v_pk_fma_f32 v[106:107], v[92:93], v[148:149], v[152:153]
	v_pk_fma_f32 v[104:105], v[86:87], v[138:139], v[104:105]
	v_pk_fma_f32 v[106:107], v[84:85], v[136:137], v[106:107]
	s_waitcnt lgkmcnt(3)
	v_pk_fma_f32 v[104:105], v[192:193], v[98:99], v[104:105]
	v_pk_fma_f32 v[98:99], v[76:77], v[148:149], v[152:153]
	v_pk_fma_f32 v[106:107], v[194:195], v[96:97], v[106:107]
	v_pk_fma_f32 v[96:97], v[78:79], v[150:151], v[154:155]
	v_pk_fma_f32 v[98:99], v[80:81], v[140:141], v[98:99]
	v_pk_fma_f32 v[96:97], v[82:83], v[142:143], v[96:97]
	s_waitcnt lgkmcnt(1)
	v_pk_fma_f32 v[98:99], v[190:191], v[108:109], v[98:99]
	v_pk_fma_f32 v[108:109], v[90:91], v[146:147], v[158:159]
	v_pk_fma_f32 v[96:97], v[188:189], v[110:111], v[96:97]
	v_pk_fma_f32 v[110:111], v[88:89], v[144:145], v[156:157]
	v_pk_fma_f32 v[108:109], v[74:75], v[130:131], v[108:109]
	v_pk_fma_f32 v[110:111], v[72:73], v[128:129], v[110:111]
	v_pk_fma_f32 v[108:109], v[184:185], v[102:103], v[108:109]
	v_pk_fma_f32 v[102:103], v[64:65], v[144:145], v[156:157]
	v_pk_fma_f32 v[110:111], v[186:187], v[100:101], v[110:111]
	v_pk_fma_f32 v[102:103], v[68:69], v[132:133], v[102:103]
	v_pk_fma_f32 v[100:101], v[66:67], v[146:147], v[158:159]
	s_waitcnt lgkmcnt(0)
	v_pk_fma_f32 v[102:103], v[182:183], v[112:113], v[102:103]
	v_mov_b32_e32 v112, v110
	v_mov_b32_e32 v110, v108
	v_add_u32_e32 v108, 0x80, v221
	v_add_u32_e32 v113, s41, v108
	v_pk_fma_f32 v[100:101], v[70:71], v[134:135], v[100:101]
	v_cmp_lt_i32_e64 s[12:13], s93, v113
	v_pk_fma_f32 v[100:101], v[180:181], v[114:115], v[100:101]
	s_nop 1
	v_fmac_f32_dpp v106, v76, v140 row_shr:1 row_mask:0xf bank_mask:0xf bound_ctrl:1
	v_fmac_f32_dpp v107, v77, v141 row_shr:1 row_mask:0xf bank_mask:0xf bound_ctrl:1
	v_fmac_f32_dpp v104, v78, v142 row_shr:1 row_mask:0xf bank_mask:0xf bound_ctrl:1
	v_fmac_f32_dpp v105, v79, v143 row_shr:1 row_mask:0xf bank_mask:0xf bound_ctrl:1
	s_nop 1
	v_fmac_f32_dpp v98, v92, v136 row_shl:1 row_mask:0xf bank_mask:0xf bound_ctrl:1
	v_fmac_f32_dpp v99, v93, v137 row_shl:1 row_mask:0xf bank_mask:0xf bound_ctrl:1
	v_fmac_f32_dpp v96, v94, v138 row_shl:1 row_mask:0xf bank_mask:0xf bound_ctrl:1
	v_fmac_f32_dpp v97, v95, v139 row_shl:1 row_mask:0xf bank_mask:0xf bound_ctrl:1
	s_nop 1
	v_fmac_f32_dpp v112, v64, v132 row_shr:1 row_mask:0xf bank_mask:0xf bound_ctrl:1
	v_fmac_f32_dpp v111, v65, v133 row_shr:1 row_mask:0xf bank_mask:0xf bound_ctrl:1
	v_fmac_f32_dpp v110, v66, v134 row_shr:1 row_mask:0xf bank_mask:0xf bound_ctrl:1
	v_fmac_f32_dpp v109, v67, v135 row_shr:1 row_mask:0xf bank_mask:0xf bound_ctrl:1
	s_nop 0
	v_cndmask_b32_e64 v114, 0, v217, s[12:13]
	v_add_u32_e32 v113, v113, v114
	v_add_u32_e32 v184, -1, v113
	v_add_u32_e32 v113, 0x7f, v221
	v_cmp_gt_u32_e64 s[14:15], s92, v113
	v_cmp_gt_u32_e64 s[16:17], s74, v184
	s_and_b64 s[56:57], s[14:15], s[16:17]
	v_cndmask_b32_e64 v185, 0, v218, s[12:13]
	s_nop 1
	v_fmac_f32_dpp v102, v88, v128 row_shl:1 row_mask:0xf bank_mask:0xf bound_ctrl:1
	v_fmac_f32_dpp v103, v89, v129 row_shl:1 row_mask:0xf bank_mask:0xf bound_ctrl:1
	v_fmac_f32_dpp v100, v90, v130 row_shl:1 row_mask:0xf bank_mask:0xf bound_ctrl:1
	v_fmac_f32_dpp v101, v91, v131 row_shl:1 row_mask:0xf bank_mask:0xf bound_ctrl:1
	s_and_saveexec_b64 s[12:13], s[56:57]
	s_cbranch_execz .LBB0_1024
	v_mul_f32_e32 v113, 0xbfb8aa3b, v106
	v_exp_f32_e32 v113, v113
	v_mul_f32_e32 v114, 0xbfb8aa3b, v107
	v_exp_f32_e32 v114, v114
	v_mul_f32_e32 v115, 0xbfb8aa3b, v104
	v_add_f32_e32 v113, 1.0, v113
	v_rcp_f32_e32 v113, v113
	v_add_f32_e32 v114, 1.0, v114
	v_rcp_f32_e32 v114, v114
	v_mul_f32_e32 v106, v106, v113
	v_mul_f32_e32 v106, v112, v106
	v_exp_f32_e32 v112, v115
	v_mul_f32_e32 v113, 0xbfb8aa3b, v105
	v_exp_f32_e32 v113, v113
	v_mul_f32_e32 v107, v107, v114
	v_mul_f32_e32 v107, v111, v107
	v_add_f32_e32 v111, 1.0, v112
	v_rcp_f32_e32 v111, v111
	v_add_f32_e32 v112, 1.0, v113
	v_rcp_f32_e32 v112, v112
	v_cvt_pk_bf16_f32 v238, v106, v107
	v_mul_f32_e32 v104, v104, v111
	v_mul_f32_e32 v104, v110, v104
	v_mul_f32_e32 v105, v105, v112
	v_mul_f32_e32 v105, v109, v105
	v_cvt_pk_bf16_f32 v239, v104, v105
.LBB0_1024:
	s_or_b64 exec, exec, s[12:13]
	s_add_i32 s12, s41, 0x81
	v_add_u32_e32 v104, s12, v221
	v_cmp_lt_i32_e64 s[12:13], s93, v104
	v_cmp_gt_u32_e64 s[14:15], s92, v108
	s_nop 0
	v_cndmask_b32_e64 v105, 0, v217, s[12:13]
	v_add_u32_e32 v104, v104, v105
	v_add_u32_e32 v180, -1, v104
	v_cmp_gt_u32_e64 s[16:17], s74, v180
	s_and_b64 s[58:59], s[14:15], s[16:17]
	v_cndmask_b32_e64 v181, 0, v218, s[12:13]
	s_and_saveexec_b64 s[12:13], s[58:59]
	s_cbranch_execz .LBB0_1026
	v_pk_fma_f32 v[106:107], v[84:85], v[148:149], v[152:153]
	v_pk_fma_f32 v[104:105], v[86:87], v[150:151], v[154:155]
	v_pk_fma_f32 v[92:93], v[92:93], v[140:141], v[106:107]
	v_pk_fma_f32 v[94:95], v[94:95], v[142:143], v[104:105]
	v_pk_fma_f32 v[92:93], v[80:81], v[136:137], v[92:93]
	v_pk_fma_f32 v[104:105], v[74:75], v[146:147], v[158:159]
	v_pk_fma_f32 v[106:107], v[72:73], v[144:145], v[156:157]
	v_pk_fma_f32 v[90:91], v[90:91], v[134:135], v[104:105]
	v_mul_f32_e32 v104, 0xbfb8aa3b, v92
	v_exp_f32_e32 v104, v104
	v_mul_f32_e32 v105, 0xbfb8aa3b, v93
	v_exp_f32_e32 v105, v105
	v_pk_fma_f32 v[88:89], v[88:89], v[132:133], v[106:107]
	v_add_f32_e32 v104, 1.0, v104
	v_rcp_f32_e32 v104, v104
	v_add_f32_e32 v105, 1.0, v105
	v_rcp_f32_e32 v105, v105
	v_pk_fma_f32 v[94:95], v[82:83], v[138:139], v[94:95]
	v_pk_fma_f32 v[88:89], v[68:69], v[128:129], v[88:89]
	v_mul_f32_e32 v92, v92, v104
	v_mul_f32_e32 v88, v88, v92
	v_mul_f32_e32 v92, v93, v105
	v_mul_f32_e32 v93, 0xbfb8aa3b, v94
	v_exp_f32_e32 v93, v93
	v_mul_f32_e32 v104, 0xbfb8aa3b, v95
	v_exp_f32_e32 v104, v104
	v_mul_f32_e32 v89, v89, v92
	v_add_f32_e32 v92, 1.0, v93
	v_rcp_f32_e32 v92, v92
	v_add_f32_e32 v93, 1.0, v104
	v_rcp_f32_e32 v93, v93
	v_pk_fma_f32 v[90:91], v[70:71], v[130:131], v[90:91]
	v_cvt_pk_bf16_f32 v240, v88, v89
	v_mul_f32_e32 v89, v94, v92
	v_mul_f32_e32 v89, v90, v89
	v_mul_f32_e32 v90, v95, v93
	v_mul_f32_e32 v90, v91, v90
	v_cvt_pk_bf16_f32 v241, v89, v90
; __device__ __forceinline__ unsigned pk2(float lo, float hi) { unsigned r; asm("v_cvt_pk_bf16_f32 %0, %1, %2" : "=v"(r) : "v"(lo), "v"(hi)); return r; }
; __device__ __forceinline__ float silu_(float x) { return x * fast_sigmoid(x); }
;     __device__ __forceinline__ void operator()(const f32x4 (&acc)[2][2][4][2], const Unit& u, int wr, int wc, int fr, int fq) const {
;     ...
;                 for (int m = 0; m < 4; ++m) {
;                     const int lr = 128 * ai + 64 * wr + 4 * fr + m;
;                     const int R = 254 * u.pm + lr;
;                     const int b = R >= (H2_BSTRIDE + 1) ? 1 : 0;
;                     const int t = R - 1 - H2_BSTRIDE * b;
;                     const bool valid = lr >= 1 && lr <= 254 && t >= 0 && t < S;
;                     if (valid) {
;                         u32x2 w;
;                         w.x = pk2(silu_(cvv[m][0][0]) * cvv[m][1][0], silu_(cvv[m][0][1]) * cvv[m][1][1]);
;                         w.y = pk2(silu_(cvv[m][0][2]) * cvv[m][1][2], silu_(cvv[m][0][3]) * cvv[m][1][3]);
;                         *(u32x2*)(act + (size_t)(b * S + t) * DFF + chg) = w;
.LBB0_1026:
	s_or_b64 exec, exec, s[12:13]
	v_add_u32_e32 v88, 0x82, v221
	v_add_u32_e32 v89, s41, v88
	v_cmp_lt_i32_e64 s[12:13], s93, v89
	v_cmp_gt_u32_e64 s[14:15], s95, v88
	s_nop 0
	v_cndmask_b32_e64 v90, 0, v217, s[12:13]
	v_add_u32_e32 v89, v89, v90
	v_add_u32_e32 v182, -1, v89
	v_cmp_gt_u32_e64 s[16:17], s74, v182
	s_and_b64 s[60:61], s[14:15], s[16:17]
	v_cndmask_b32_e64 v183, 0, v218, s[12:13]
	s_and_saveexec_b64 s[12:13], s[60:61]
	s_cbranch_execz .LBB0_1028
	v_pk_fma_f32 v[80:81], v[80:81], v[148:149], v[152:153]
	v_pk_fma_f32 v[68:69], v[68:69], v[144:145], v[156:157]
	v_pk_fma_f32 v[80:81], v[84:85], v[140:141], v[80:81]
	v_pk_fma_f32 v[68:69], v[72:73], v[132:133], v[68:69]
	v_pk_fma_f32 v[76:77], v[76:77], v[136:137], v[80:81]
	v_pk_fma_f32 v[70:71], v[70:71], v[146:147], v[158:159]
	v_mul_f32_e32 v72, 0xbfb8aa3b, v76
	v_exp_f32_e32 v72, v72
	v_mul_f32_e32 v73, 0xbfb8aa3b, v77
	v_pk_fma_f32 v[70:71], v[74:75], v[134:135], v[70:71]
	v_exp_f32_e32 v73, v73
	v_pk_fma_f32 v[66:67], v[66:67], v[130:131], v[70:71]
	v_add_f32_e32 v70, 1.0, v72
	v_pk_fma_f32 v[82:83], v[82:83], v[150:151], v[154:155]
	v_rcp_f32_e32 v70, v70
	v_pk_fma_f32 v[82:83], v[86:87], v[142:143], v[82:83]
	v_add_f32_e32 v71, 1.0, v73
	v_pk_fma_f32 v[78:79], v[78:79], v[138:139], v[82:83]
	v_rcp_f32_e32 v71, v71
	v_pk_fma_f32 v[64:65], v[64:65], v[128:129], v[68:69]
	v_mul_f32_e32 v69, 0xbfb8aa3b, v78
	v_mul_f32_e32 v68, v76, v70
	v_exp_f32_e32 v69, v69
	v_mul_f32_e32 v70, 0xbfb8aa3b, v79
	v_exp_f32_e32 v70, v70
	v_mul_f32_e32 v64, v64, v68
	v_mul_f32_e32 v68, v77, v71
	v_mul_f32_e32 v65, v65, v68
	v_add_f32_e32 v68, 1.0, v69
	v_rcp_f32_e32 v68, v68
	v_add_f32_e32 v69, 1.0, v70
	v_rcp_f32_e32 v69, v69
	v_cvt_pk_bf16_f32 v242, v64, v65
	v_mul_f32_e32 v65, v78, v68
	v_mul_f32_e32 v65, v66, v65
	v_mul_f32_e32 v66, v79, v69
	v_mul_f32_e32 v66, v67, v66
	v_cvt_pk_bf16_f32 v243, v65, v66
.LBB0_1028:
	s_or_b64 exec, exec, s[12:13]
	v_add_u32_e32 v64, 0x83, v221
	v_add_u32_e32 v65, s41, v64
	v_cmp_lt_i32_e64 s[12:13], s93, v65
	v_cmp_gt_u32_e64 s[14:15], s95, v64
	s_nop 0
	v_cndmask_b32_e64 v66, 0, v217, s[12:13]
	v_add_u32_e32 v65, v65, v66
	v_add_u32_e32 v128, -1, v65
	v_cmp_gt_u32_e64 s[16:17], s74, v128
	s_and_b64 s[14:15], s[14:15], s[16:17]
	v_cndmask_b32_e64 v129, 0, v218, s[12:13]
	s_and_saveexec_b64 s[12:13], s[14:15]
	s_cbranch_execz .LBB0_1030
	v_mul_f32_e32 v64, 0xbfb8aa3b, v98
	v_mul_f32_e32 v65, 0xbfb8aa3b, v99
	v_exp_f32_e32 v64, v64
	v_exp_f32_e32 v65, v65
	v_mul_f32_e32 v66, 0xbfb8aa3b, v96
	v_mul_f32_e32 v67, 0xbfb8aa3b, v97
	v_exp_f32_e32 v66, v66
	v_exp_f32_e32 v67, v67
	v_add_f32_e32 v64, 1.0, v64
	v_add_f32_e32 v65, 1.0, v65
	v_rcp_f32_e32 v64, v64
	v_rcp_f32_e32 v65, v65
	v_add_f32_e32 v66, 1.0, v66
	v_add_f32_e32 v67, 1.0, v67
	v_rcp_f32_e32 v66, v66
	v_rcp_f32_e32 v67, v67
	v_mul_f32_e32 v64, v98, v64
	v_mul_f32_e32 v65, v99, v65
	v_mul_f32_e32 v64, v102, v64
	v_mul_f32_e32 v65, v103, v65
	v_cvt_pk_bf16_f32 v244, v64, v65
	v_mul_f32_e32 v65, v96, v66
	v_mul_f32_e32 v66, v97, v67
	v_mul_f32_e32 v65, v100, v65
	v_mul_f32_e32 v66, v101, v66
	v_cvt_pk_bf16_f32 v245, v65, v66
; #define LAS __attribute__((address_space(3)))
; #define CG_LOADW(N) do { _Pragma("unroll") for (int bj = 0; bj < 2; ++bj) { const int ch = 128 * u.pn + 32 * wc + 16 * (N) + 4 * fq + bj * DFF; \
;             wq[N][bj][0] = *(const f32x4*)(cw + ch); wq[N][bj][1] = *(const f32x4*)(cw + DUP + ch); wq[N][bj][2] = *(const f32x4*)(cw + 2 * DUP + ch); wq[N][bj][3] = *(const f32x4*)(cbias + ch); } } while (0)
;     __device__ __forceinline__ void operator()(const f32x4 (&acc)[2][2][4][2], const Unit& u, int wr, int wc, int fr, int fq) const {
;     ...
;         for (int n = 0; n < 2; ++n) {
;             const int chg = 128 * u.pn + 32 * wc + 16 * n + 4 * fq;
;             if (n == 1) CG_LOADW(1);
;             f32x4 w0[2], w1[2], w2[2], bb[2], w0m[2], w2m[2];
; #pragma unroll
;             for (int bj = 0; bj < 2; ++bj) {
;                 w0[bj] = wq[n][bj][0]; w1[bj] = wq[n][bj][1]; w2[bj] = wq[n][bj][2]; bb[bj] = wq[n][bj][3];
;                 w0m[bj] = (fr == 0) ? w0[bj] : (f32x4){0.f, 0.f, 0.f, 0.f}; w2m[bj] = (fr == 15) ? w2[bj] : (f32x4){0.f, 0.f, 0.f, 0.f};
;             }
; #pragma unroll
;             for (int ai = 0; ai < 2; ++ai) {
;                 const int s = 2 * ai + wr;
;                 f32x4 xp[2], xn[2];
; #pragma unroll
;                 for (int bj = 0; bj < 2; ++bj) {
;                     xp[bj] = *(const LAS f32x4*)(X + ((((s + 3) & 3) * 2 + 1) * 2 + bj) * 128 + 32 * wc + 16 * n + 4 * fq);
;                     xn[bj] = *(const LAS f32x4*)(X + ((((s + 1) & 3) * 2 + 0) * 2 + bj) * 128 + 32 * wc + 16 * n + 4 * fq);
;                 }
;                 f32x4 cvv[4][2];
; #pragma unroll
;                 for (int bj = 0; bj < 2; ++bj) {
;                     const f32x4 a0 = acc[ai][bj][0][n], a1 = acc[ai][bj][1][n], a2 = acc[ai][bj][2][n], a3 = acc[ai][bj][3][n];
;                     f32x4 c0 = bb[bj] + w1[bj] * a0 + w2[bj] * a1 + w0m[bj] * xp[bj];
;                     f32x4 c1 = bb[bj] + w1[bj] * a1 + w0[bj] * a0 + w2[bj] * a2;
;                     f32x4 c2 = bb[bj] + w1[bj] * a2 + w0[bj] * a1 + w2[bj] * a3;
;                     f32x4 c3 = bb[bj] + w1[bj] * a3 + w0[bj] * a2 + w2m[bj] * xn[bj];
;                     DPP_FMAC4(c0, a3, w0[bj], "row_shr:1");
;                     DPP_FMAC4(c3, a0, w2[bj], "row_shl:1");
;                     cvv[0][bj] = c0; cvv[1][bj] = c1; cvv[2][bj] = c2; cvv[3][bj] = c3;
;                 }
.LBB0_1030:
	s_or_b64 exec, exec, s[12:13]
	s_ashr_i32 s47, s46, 31
	v_lshl_add_u64 v[66:67], v[168:169], 0, s[46:47]
	v_add3_u32 v64, v168, s46, 16
	v_lshlrev_b64 v[66:67], 2, v[66:67]
	v_ashrrev_i32_e32 v65, 31, v64
	v_lshl_add_u64 v[68:69], s[20:21], 0, v[66:67]
	v_lshlrev_b64 v[64:65], 2, v[64:65]
	v_lshl_add_u64 v[92:93], s[22:23], 0, v[66:67]
	v_add_co_u32_e64 v66, s[12:13], s72, v68
	v_lshl_add_u64 v[84:85], s[36:37], 0, v[64:65]
	v_lshl_add_u64 v[64:65], s[38:39], 0, v[64:65]
	v_addc_co_u32_e64 v67, s[12:13], 0, v69, s[12:13]
	global_load_dwordx4 v[76:79], v[68:69], off offset:64
	global_load_dwordx4 v[80:83], v[84:85], off
	global_load_dwordx4 v[72:75], v[64:65], off
	global_load_dwordx4 v[88:91], v[92:93], off offset:64
	s_waitcnt vmcnt(3)
	v_cndmask_b32_e32 v109, 0, v79, vcc
	global_load_dwordx4 v[68:71], v[66:67], off offset:3136
	v_add_co_u32_e64 v64, s[12:13], s72, v64
	s_waitcnt vmcnt(1)
	v_pk_fma_f32 v[120:121], v[62:63], v[82:83], v[90:91]
	v_addc_co_u32_e64 v65, s[12:13], 0, v65, s[12:13]
	v_add_co_u32_e64 v84, s[12:13], s72, v84
	global_load_dwordx4 v[64:67], v[64:65], off offset:3072
	s_nop 0
	v_addc_co_u32_e64 v85, s[12:13], 0, v85, s[12:13]
	v_add_co_u32_e64 v92, s[12:13], s72, v92
	global_load_dwordx4 v[84:87], v[84:85], off offset:3072
	s_nop 0
	v_addc_co_u32_e64 v93, s[12:13], 0, v93, s[12:13]
	global_load_dwordx4 v[92:95], v[92:93], off offset:3136
	ds_read_b128 v[112:115], v219 offset:1088
	ds_read_b128 v[116:119], v219 offset:1600
	ds_read_b128 v[130:133], v220 offset:64
	ds_read_b128 v[134:137], v220 offset:576
	v_pk_fma_f32 v[122:123], v[60:61], v[80:81], v[88:89]
	v_pk_fma_f32 v[124:125], v[46:47], v[82:83], v[90:91]
	v_pk_fma_f32 v[126:127], v[44:45], v[80:81], v[88:89]
	v_cndmask_b32_e32 v108, 0, v78, vcc
	v_cndmask_b32_e32 v111, 0, v77, vcc
	v_cndmask_b32_e32 v110, 0, v76, vcc
	v_cndmask_b32_e64 v105, 0, v75, s[8:9]
	v_cndmask_b32_e64 v104, 0, v74, s[8:9]
	v_cndmask_b32_e64 v107, 0, v73, s[8:9]
	v_cndmask_b32_e64 v106, 0, v72, s[8:9]
	v_pk_fma_f32 v[120:121], v[54:55], v[74:75], v[120:121]
	v_pk_fma_f32 v[122:123], v[52:53], v[72:73], v[122:123]
	v_pk_fma_f32 v[138:139], v[50:51], v[78:79], v[124:125]
	v_pk_fma_f32 v[126:127], v[48:49], v[76:77], v[126:127]
	s_waitcnt lgkmcnt(3)
	v_pk_fma_f32 v[120:121], v[108:109], v[114:115], v[120:121]
	v_pk_fma_f32 v[124:125], v[110:111], v[112:113], v[122:123]
	s_waitcnt lgkmcnt(1)
	v_pk_fma_f32 v[112:113], v[104:105], v[132:133], v[138:139]
	v_pk_fma_f32 v[114:115], v[106:107], v[130:131], v[126:127]
	s_nop 1
	v_fmac_f32_dpp v124, v44, v76 row_shr:1 row_mask:0xf bank_mask:0xf bound_ctrl:1
	v_fmac_f32_dpp v125, v45, v77 row_shr:1 row_mask:0xf bank_mask:0xf bound_ctrl:1
	v_fmac_f32_dpp v120, v46, v78 row_shr:1 row_mask:0xf bank_mask:0xf bound_ctrl:1
	v_fmac_f32_dpp v121, v47, v79 row_shr:1 row_mask:0xf bank_mask:0xf bound_ctrl:1
	s_waitcnt vmcnt(3)
	v_cndmask_b32_e32 v101, 0, v71, vcc
	v_cndmask_b32_e32 v100, 0, v70, vcc
	v_cndmask_b32_e32 v103, 0, v69, vcc
	v_cndmask_b32_e32 v102, 0, v68, vcc
	s_nop 1
	v_fmac_f32_dpp v114, v60, v72 row_shl:1 row_mask:0xf bank_mask:0xf bound_ctrl:1
	v_fmac_f32_dpp v115, v61, v73 row_shl:1 row_mask:0xf bank_mask:0xf bound_ctrl:1
	v_fmac_f32_dpp v112, v62, v74 row_shl:1 row_mask:0xf bank_mask:0xf bound_ctrl:1
	v_fmac_f32_dpp v113, v63, v75 row_shl:1 row_mask:0xf bank_mask:0xf bound_ctrl:1
	s_waitcnt vmcnt(2)
	v_cndmask_b32_e64 v97, 0, v67, s[8:9]
	v_cndmask_b32_e64 v96, 0, v66, s[8:9]
	v_cndmask_b32_e64 v99, 0, v65, s[8:9]
	v_cndmask_b32_e64 v98, 0, v64, s[8:9]
	s_waitcnt vmcnt(0)
	v_pk_fma_f32 v[140:141], v[58:59], v[86:87], v[94:95]
	v_pk_fma_f32 v[142:143], v[56:57], v[84:85], v[92:93]
	v_pk_fma_f32 v[144:145], v[34:35], v[86:87], v[94:95]
	v_pk_fma_f32 v[146:147], v[32:33], v[84:85], v[92:93]
	v_pk_fma_f32 v[122:123], v[42:43], v[66:67], v[140:141]
	v_pk_fma_f32 v[126:127], v[40:41], v[64:65], v[142:143]
	v_pk_fma_f32 v[130:131], v[38:39], v[70:71], v[144:145]
	v_pk_fma_f32 v[132:133], v[36:37], v[68:69], v[146:147]
	v_pk_fma_f32 v[122:123], v[100:101], v[118:119], v[122:123]
	v_pk_fma_f32 v[126:127], v[102:103], v[116:117], v[126:127]
	s_waitcnt lgkmcnt(0)
	v_pk_fma_f32 v[116:117], v[96:97], v[136:137], v[130:131]
	v_pk_fma_f32 v[118:119], v[98:99], v[134:135], v[132:133]
	s_nop 1
	v_fmac_f32_dpp v126, v32, v68 row_shr:1 row_mask:0xf bank_mask:0xf bound_ctrl:1
	v_fmac_f32_dpp v127, v33, v69 row_shr:1 row_mask:0xf bank_mask:0xf bound_ctrl:1
	v_fmac_f32_dpp v122, v34, v70 row_shr:1 row_mask:0xf bank_mask:0xf bound_ctrl:1
	v_fmac_f32_dpp v123, v35, v71 row_shr:1 row_mask:0xf bank_mask:0xf bound_ctrl:1
	s_nop 0
	s_nop 1
	v_fmac_f32_dpp v118, v56, v64 row_shl:1 row_mask:0xf bank_mask:0xf bound_ctrl:1
	v_fmac_f32_dpp v119, v57, v65 row_shl:1 row_mask:0xf bank_mask:0xf bound_ctrl:1
	v_fmac_f32_dpp v116, v58, v66 row_shl:1 row_mask:0xf bank_mask:0xf bound_ctrl:1
	v_fmac_f32_dpp v117, v59, v67 row_shl:1 row_mask:0xf bank_mask:0xf bound_ctrl:1
	s_and_saveexec_b64 s[8:9], s[48:49]
	s_cbranch_execnz .LBB0_1042
	s_or_b64 exec, exec, s[8:9]
	s_and_saveexec_b64 s[8:9], s[50:51]
	s_cbranch_execnz .LBB0_1043
